# mix2 attention epilogue: O tile scaled, transposed through a private per-wave LDS slab and stored with 4 dwordx4 per wave instead of 32 short stores
# baseline (speedup 1.0000x reference)
.LBB0_1432:
	s_or_b64 exec, exec, s[12:13]
	s_lshl_b64 s[12:13], s[20:21], 1
	s_add_u32 s12, s6, s12
	s_addc_u32 s13, s7, s13
	s_waitcnt lgkmcnt(0)
	ds_read_b128 v[36:39], v169
	ds_read_b128 v[40:43], v169 offset:32
	ds_read_b128 v[44:47], v169 offset:64
	ds_read_b128 v[48:51], v169 offset:96
	v_mbcnt_lo_u32_b32 v52, -1, 0
	v_mbcnt_hi_u32_b32 v52, -1, v52
	v_readlane_b32 s28, v252, 23
	v_readlane_b32 s29, v254, 49
	v_and_b32_e32 v53, 7, v52
	v_lshlrev_b32_e32 v58, 4, v53
	v_mov_b32_e32 v59, v64
	v_lshl_add_u64 v[32:33], s[12:13], 0, v[58:59]
	s_lshl_b32 s28, s28, 12
	s_add_i32 s28, s28, 0x1c400
	v_lshlrev_b32_e32 v55, 4, v52
	v_add_u32_e32 v55, s28, v55
	v_lshlrev_b32_e32 v53, 1, v145
	v_lshl_add_u32 v53, v164, 7, v53
	v_add_u32_e32 v53, s28, v53
	v_lshrrev_b32_e32 v54, 3, v52
	v_add_u32_e32 v54, s29, v54
	s_waitcnt lgkmcnt(0)
	v_mul_f32_e32 v56, v0, v36
	v_mul_f32_e32 v57, v16, v36
	v_cvt_pk_bf16_f32 v56, v56, v57
	ds_write_b16 v53, v56
	ds_write_b16_d16_hi v53, v56 offset:64
	v_mul_f32_e32 v56, v1, v37
	v_mul_f32_e32 v57, v17, v37
	v_cvt_pk_bf16_f32 v56, v56, v57
	ds_write_b16 v53, v56 offset:128
	ds_write_b16_d16_hi v53, v56 offset:192
	v_mul_f32_e32 v56, v2, v38
	v_mul_f32_e32 v57, v18, v38
	v_cvt_pk_bf16_f32 v56, v56, v57
	ds_write_b16 v53, v56 offset:256
	ds_write_b16_d16_hi v53, v56 offset:320
	v_mul_f32_e32 v56, v3, v39
	v_mul_f32_e32 v57, v19, v39
	v_cvt_pk_bf16_f32 v56, v56, v57
	ds_write_b16 v53, v56 offset:384
	ds_write_b16_d16_hi v53, v56 offset:448
	v_mul_f32_e32 v56, v4, v40
	v_mul_f32_e32 v57, v20, v40
	v_cvt_pk_bf16_f32 v56, v56, v57
	ds_write_b16 v53, v56 offset:1024
	ds_write_b16_d16_hi v53, v56 offset:1088
	v_mul_f32_e32 v56, v5, v41
	v_mul_f32_e32 v57, v21, v41
	v_cvt_pk_bf16_f32 v56, v56, v57
	ds_write_b16 v53, v56 offset:1152
	ds_write_b16_d16_hi v53, v56 offset:1216
	v_mul_f32_e32 v56, v6, v42
	v_mul_f32_e32 v57, v22, v42
	v_cvt_pk_bf16_f32 v56, v56, v57
	ds_write_b16 v53, v56 offset:1280
	ds_write_b16_d16_hi v53, v56 offset:1344
	v_mul_f32_e32 v56, v7, v43
	v_mul_f32_e32 v57, v23, v43
	v_cvt_pk_bf16_f32 v56, v56, v57
	ds_write_b16 v53, v56 offset:1408
	ds_write_b16_d16_hi v53, v56 offset:1472
	v_mul_f32_e32 v56, v8, v44
	v_mul_f32_e32 v57, v24, v44
	v_cvt_pk_bf16_f32 v56, v56, v57
	ds_write_b16 v53, v56 offset:2048
	ds_write_b16_d16_hi v53, v56 offset:2112
	v_mul_f32_e32 v56, v9, v45
	v_mul_f32_e32 v57, v25, v45
	v_cvt_pk_bf16_f32 v56, v56, v57
	ds_write_b16 v53, v56 offset:2176
	ds_write_b16_d16_hi v53, v56 offset:2240
	v_mul_f32_e32 v56, v10, v46
	v_mul_f32_e32 v57, v26, v46
	v_cvt_pk_bf16_f32 v56, v56, v57
	ds_write_b16 v53, v56 offset:2304
	ds_write_b16_d16_hi v53, v56 offset:2368
	v_mul_f32_e32 v56, v11, v47
	v_mul_f32_e32 v57, v27, v47
	v_cvt_pk_bf16_f32 v56, v56, v57
	ds_write_b16 v53, v56 offset:2432
	ds_write_b16_d16_hi v53, v56 offset:2496
	v_mul_f32_e32 v56, v12, v48
	v_mul_f32_e32 v57, v28, v48
	v_cvt_pk_bf16_f32 v56, v56, v57
	ds_write_b16 v53, v56 offset:3072
	ds_write_b16_d16_hi v53, v56 offset:3136
	v_mul_f32_e32 v56, v13, v49
	v_mul_f32_e32 v57, v29, v49
	v_cvt_pk_bf16_f32 v56, v56, v57
	ds_write_b16 v53, v56 offset:3200
	ds_write_b16_d16_hi v53, v56 offset:3264
	v_mul_f32_e32 v56, v14, v50
	v_mul_f32_e32 v57, v30, v50
	v_cvt_pk_bf16_f32 v56, v56, v57
	ds_write_b16 v53, v56 offset:3328
	ds_write_b16_d16_hi v53, v56 offset:3392
	v_mul_f32_e32 v56, v15, v51
	v_mul_f32_e32 v57, v31, v51
	v_cvt_pk_bf16_f32 v56, v56, v57
	ds_write_b16 v53, v56 offset:3456
	ds_write_b16_d16_hi v53, v56 offset:3520
	s_waitcnt lgkmcnt(0)
	ds_read_b128 v[0:3], v55
	ds_read_b128 v[4:7], v55 offset:1024
	ds_read_b128 v[8:11], v55 offset:2048
	ds_read_b128 v[12:15], v55 offset:3072
	v_mov_b32_e32 v56, v54
	v_cmp_gt_u32_e32 vcc, s66, v56
	v_add_u32_e32 v60, s64, v56
	v_ashrrev_i32_e32 v61, 31, v60
	v_lshlrev_b64 v[60:61], 11, v[60:61]
	v_lshl_add_u64 v[60:61], v[32:33], 0, v[60:61]
	s_and_saveexec_b64 s[28:29], vcc
	s_waitcnt lgkmcnt(3)
	global_store_dwordx4 v[60:61], v[0:3], off
	s_or_b64 exec, exec, s[28:29]
	v_add_u32_e32 v56, 8, v54
	v_cmp_gt_u32_e32 vcc, s66, v56
	v_add_u32_e32 v60, s64, v56
	v_ashrrev_i32_e32 v61, 31, v60
	v_lshlrev_b64 v[60:61], 11, v[60:61]
	v_lshl_add_u64 v[60:61], v[32:33], 0, v[60:61]
	s_and_saveexec_b64 s[28:29], vcc
	s_waitcnt lgkmcnt(2)
	global_store_dwordx4 v[60:61], v[4:7], off
	s_or_b64 exec, exec, s[28:29]
	v_add_u32_e32 v56, 16, v54
	v_cmp_gt_u32_e32 vcc, s66, v56
	v_add_u32_e32 v60, s64, v56
	v_ashrrev_i32_e32 v61, 31, v60
	v_lshlrev_b64 v[60:61], 11, v[60:61]
	v_lshl_add_u64 v[60:61], v[32:33], 0, v[60:61]
	s_and_saveexec_b64 s[28:29], vcc
	s_waitcnt lgkmcnt(1)
	global_store_dwordx4 v[60:61], v[8:11], off
	s_or_b64 exec, exec, s[28:29]
	v_add_u32_e32 v56, 24, v54
	v_cmp_gt_u32_e32 vcc, s66, v56
	v_add_u32_e32 v60, s64, v56
	v_ashrrev_i32_e32 v61, 31, v60
	v_lshlrev_b64 v[60:61], 11, v[60:61]
	v_lshl_add_u64 v[60:61], v[32:33], 0, v[60:61]
	s_and_saveexec_b64 s[28:29], vcc
	s_waitcnt lgkmcnt(0)
	global_store_dwordx4 v[60:61], v[12:15], off
	s_or_b64 exec, exec, s[28:29]
	s_mov_b64 s[12:13], 0
	s_branch .LBB0_1278
